# adds a straight-line squared-ReLU epilogue for the up GEMM (same operations, no per-chunk mode dispatch) on top of the tile-order changes
# speedup vs baseline: 1.0079x; 1.0079x over previous
;     __host__ __device__ bool next(int i, Unit& u) const {
;         const long L = (long)i * G + c; if (L >= nwg) return false;
;         int wgid = (int)L; { const int q = nwg / NXCD, r = nwg % NXCD, xcd = wgid % NXCD, off = wgid / NXCD; wgid = (xcd < r ? xcd * (q + 1) : r * (q + 1) + (xcd - r) * q) + off; }
;         const int nig = WGM * nN, gid = wgid / nig, fm = gid * WGM, gsz = (nM - fm) < WGM ? (nM - fm) : WGM;
;         u.pm = fm + ((wgid % nig) % gsz); u.pn = (wgid % nig) / gsz; return true;
.LBB0_237:
	s_lshr_b32 s78, s55, 8
	s_mul_i32 s12, s78, 0x60
	v_lshl_add_u32 v0, s36, 6, v12
	s_cmp_lt_i32 s54, s12
	s_cselect_b64 s[8:9], -1, 0
	s_cmp_ge_i32 s54, s12
	v_readfirstlane_b32 s30, v0
	s_cbranch_scc1 .LBB0_239
	s_lshr_b32 s33, s55, 6
	v_cvt_f32_u32_e32 v1, s33
	s_ashr_i32 s15, s54, 31
	s_lshr_b32 s15, s15, 29
	s_add_i32 s15, s54, s15
	v_rcp_iflag_f32_e32 v1, v1
	s_ashr_i32 s31, s15, 3
	s_and_b32 s15, s15, -8
	s_sub_i32 s15, s54, s15
	v_mul_f32_e32 v1, 0x4f7ffffe, v1
	v_cvt_u32_f32_e32 v1, v1
	s_lshr_b32 s14, s12, 3
	s_lshr_b32 s34, s15, 31
	s_or_b32 s14, s14, s34
	s_sub_i32 s34, 0, s33
	v_readfirstlane_b32 s35, v1
	s_mul_i32 s14, s14, s15
	s_mul_i32 s34, s34, s35
	s_add_i32 s14, s14, s31
	s_mul_hi_u32 s34, s35, s34
	s_abs_i32 s31, s14
	s_add_i32 s35, s35, s34
	s_mul_hi_u32 s34, s31, s35
	s_mul_i32 s35, s34, s33
	s_sub_i32 s31, s31, s35
	s_ashr_i32 s15, s14, 31
	s_add_i32 s35, s34, 1
	s_sub_i32 s38, s31, s33
	s_cmp_ge_u32 s31, s33
	s_cselect_b32 s34, s35, s34
	s_cselect_b32 s31, s38, s31
	s_add_i32 s35, s34, 1
	s_cmp_ge_u32 s31, s33
	s_cselect_b32 s31, s35, s34
	s_xor_b32 s31, s31, s15
	s_sub_i32 s15, s31, s15
	s_lshl_b32 s31, s15, 2
	s_sub_i32 s34, 0x60, s31
	s_min_i32 s34, s34, 4
	s_mul_i32 s15, s15, s33
	s_sext_i32_i16 s33, s34
	v_cvt_f32_i32_e32 v1, s33
	s_sub_i32 s35, s14, s15
	s_sext_i32_i16 s14, s35
	v_cvt_f32_i32_e32 v2, s14
	v_rcp_iflag_f32_e32 v3, v1
	s_xor_b32 s14, s14, s33
	s_ashr_i32 s14, s14, 30
	s_or_b32 s33, s14, 1
	v_mul_f32_e32 v3, v2, v3
	v_trunc_f32_e32 v3, v3
	v_fma_f32 v2, -v3, v1, v2
	v_cvt_i32_f32_e32 v3, v3
	v_cmp_ge_f32_e64 s[14:15], |v2|, |v1|
	s_and_b64 s[14:15], s[14:15], exec
	s_cselect_b32 s14, s33, 0
	v_readfirstlane_b32 s15, v3
	s_add_i32 s14, s15, s14
	s_sext_i32_i16 s52, s14
	s_mul_i32 s14, s14, s34
	s_sub_i32 s14, s35, s14
	s_sext_i32_i16 s14, s14
	s_add_i32 s57, s31, s14
	s_lshl_b32 s14, 1, s56
	s_and_b32 s14, s14, 32
	s_cmp_lg_u32 s14, 0
	s_cbranch_scc0 .Lrev_cur_skip
	s_sub_i32 s57, 0x5f, s57

;     __host__ __device__ bool next(int i, Unit& u) const {
;         const long L = (long)i * G + c; if (L >= nwg) return false;
;         int wgid = (int)L; { const int q = nwg / NXCD, r = nwg % NXCD, xcd = wgid % NXCD, off = wgid / NXCD; wgid = (xcd < r ? xcd * (q + 1) : r * (q + 1) + (xcd - r) * q) + off; }
;         const int nig = WGM * nN, gid = wgid / nig, fm = gid * WGM, gsz = (nM - fm) < WGM ? (nM - fm) : WGM;
;         u.pm = fm + ((wgid % nig) % gsz); u.pn = (wgid % nig) / gsz; return true;
; template <class EpiT, class Sched, bool ALIGN_EPI = true>
; __device__ __forceinline__ void gemm_phase(LAS unsigned char* lds, const Gemm g, const Sched& S, const EpiT& E, const int tid) {
;     ...
;         const bool has_next = S.next(ui + 1, nxt);
.LBB0_245:
	s_add_i32 s79, s79, 1
	s_mul_i32 s0, s79, s75
	s_mul_hi_u32 s1, s79, s37
	s_add_i32 s1, s1, s0
	s_mul_i32 s0, s79, s37
	s_add_u32 s28, s0, s54
	s_addc_u32 s29, s1, s77
	v_mov_b64_e32 v[0:1], s[12:13]
	v_cmp_ge_i64_e32 vcc, s[28:29], v[0:1]
	v_cmp_lt_i64_e64 s[0:1], s[28:29], v[0:1]
	s_cbranch_vccnz .LBB0_247
	s_ashr_i32 s15, s28, 31
	s_lshr_b32 s15, s15, 29
	s_add_i32 s15, s28, s15
	s_ashr_i32 s29, s15, 3
	s_and_b32 s15, s15, -8
	s_sub_i32 s15, s28, s15
	s_lshr_b32 s28, s15, 31
	s_or_b32 s28, s78, s28
	s_mul_i32 s15, s28, s15
	s_add_i32 s15, s15, s29
	s_abs_i32 s29, s15
	s_mul_hi_u32 s30, s29, s80
	s_mul_i32 s31, s30, s76
	s_sub_i32 s29, s29, s31
	s_ashr_i32 s28, s15, 31
	s_add_i32 s31, s30, 1
	s_sub_i32 s33, s29, s76
	s_cmp_ge_u32 s29, s76
	s_cselect_b32 s30, s31, s30
	s_cselect_b32 s29, s33, s29
	s_add_i32 s31, s30, 1
	s_cmp_ge_u32 s29, s76
	s_cselect_b32 s29, s31, s30
	s_xor_b32 s29, s29, s28
	s_sub_i32 s28, s29, s28
	s_lshl_b32 s29, s28, 2
	s_sub_i32 s30, 0x60, s29
	s_min_i32 s30, s30, 4
	s_abs_i32 s31, s30
	v_cvt_f32_u32_e32 v0, s31
	s_sub_i32 s38, 0, s31
	s_mul_i32 s28, s28, s76
	s_sub_i32 s28, s15, s28
	v_rcp_iflag_f32_e32 v0, v0
	s_abs_i32 s33, s28
	s_xor_b32 s15, s28, s30
	s_ashr_i32 s15, s15, 31
	v_mul_f32_e32 v0, 0x4f7ffffe, v0
	v_cvt_u32_f32_e32 v0, v0
	s_nop 0
	v_readfirstlane_b32 s39, v0
	s_mul_i32 s38, s38, s39
	s_mul_hi_u32 s38, s39, s38
	s_add_i32 s39, s39, s38
	s_mul_hi_u32 s38, s33, s39
	s_mul_i32 s39, s38, s31
	s_sub_i32 s33, s33, s39
	s_add_i32 s39, s38, 1
	s_sub_i32 s40, s33, s31
	s_cmp_ge_u32 s33, s31
	s_cselect_b32 s38, s39, s38
	s_cselect_b32 s33, s40, s33
	s_add_i32 s39, s38, 1
	s_cmp_ge_u32 s33, s31
	s_cselect_b32 s31, s39, s38
	s_xor_b32 s31, s31, s15
	s_sub_i32 s15, s31, s15
	s_mul_i32 s30, s15, s30
	s_sub_i32 s28, s28, s30
	s_add_i32 s82, s28, s29
	s_lshl_b32 s30, 1, s56
	s_and_b32 s30, s30, 32
	s_cmp_lg_u32 s30, 0
	s_cbranch_scc0 .Lrev_nxt_skip
	s_sub_i32 s82, 0x5f, s82

;     __device__ __forceinline__ void operator()(const f32x4 (&acc)[2][2][4][2], const Unit& u, int wr, int wc, int fr_in, int fq_in) const {
;     ...
; #pragma unroll
;         for (int bj = 0; bj < 2; ++bj) {
;             const int c = col0 + bj * HALF;
;             f32x4 cs0 = {0.f, 0.f, 0.f, 0.f}, cs1 = cs0, bw0 = cs0, bw1 = cs0;
;             if (lnin) { const unsigned cb = (unsigned)c * 4u; cs0 = *(const f32x4*)((const char*)cs + cb); cs1 = *(const f32x4*)((const char*)cs + cb + 16u); bw0 = *(const f32x4*)((const char*)bw + cb); bw1 = *(const f32x4*)((const char*)bw + cb + 16u); }
;             bool rope = false; int i0 = 0, tw = 64; float sc = 1.f;
;             if (mode == EM_QKVA) { rope = c < 2560; i0 = (c & 127) >> 1; tw = 64; sc = c < 2048 ? QS_A : 1.f; }
;             else if (mode == EM_UQ) { const int hc = c % 192; rope = hc >= 128; i0 = (hc - 128) >> 1; tw = 32; sc = QS_B; }
.LBB0_272:
	s_and_b64 vcc, exec, s[40:41]
	s_cbranch_vccnz .LBB0_287
	v_lshlrev_b32_e32 v128, 2, v232
	global_load_dwordx4 v[164:167], v128, s[20:21]
	global_load_dwordx4 v[160:163], v128, s[20:21] offset:16
	global_load_dwordx4 v[172:175], v128, s[46:47]
	global_load_dwordx4 v[168:171], v128, s[46:47] offset:16
	s_cmp_eq_u32 s56, 1
	s_cbranch_scc1 .Lepi_relu2
	s_cmp_lt_i32 s56, 3
	s_cbranch_scc1 .LBB0_288

;     __device__ __forceinline__ void operator()(const f32x4 (&acc)[2][2][4][2], const Unit& u, int wr, int wc, int fr_in, int fq_in) const {
;     ...
;         for (int bj = 0; bj < 2; ++bj) {
;             const int c = col0 + bj * HALF;
;             f32x4 cs0 = {0.f, 0.f, 0.f, 0.f}, cs1 = cs0, bw0 = cs0, bw1 = cs0;
;             if (lnin) { const unsigned cb = (unsigned)c * 4u; cs0 = *(const f32x4*)((const char*)cs + cb); cs1 = *(const f32x4*)((const char*)cs + cb + 16u); bw0 = *(const f32x4*)((const char*)bw + cb); bw1 = *(const f32x4*)((const char*)bw + cb + 16u); }
;     ...
;                 for (int m = 0; m < 4; ++m) {
;                     const int row = row0 + ai * HALF + m * 16;
;                     f32x4 v0 = acc[ai][bj][m][0], v1 = acc[ai][bj][m][1];
;                     if (lnin) { const float mm = mu[ai * 4 + m], rr = rs[ai * 4 + m]; v0 = (v0 - cs0 * mm) * rr + bw0; v1 = (v1 - cs1 * mm) * rr + bw1; }
;                     if (mode == EM_F32) { const unsigned ob = (unsigned)(row * ldo + c) * 4u; *(f32x4*)((char*)Of + ob) = v0; *(f32x4*)((char*)Of + ob + 16u) = v1; }
;                     else {
;                         if (mode == EM_RELU2) {
; #pragma unroll
;                             for (int e = 0; e < 4; ++e) { const float a = fmaxf(v0[e], 0.f), b = fmaxf(v1[e], 0.f); v0[e] = a * a; v1[e] = b * b; }
;                         } else if (mode == EM_QKVA || mode == EM_UQ) {
;                             if (rope) {
;                                 const f32x4 cs_ = rc[m], sn = rsn[m];
;                                 f32x4 w0, w1;
;                                 w0[0] = v0[0] * cs_[0] - v0[1] * sn[0]; w0[1] = v0[1] * cs_[0] + v0[0] * sn[0];
;                                 w0[2] = v0[2] * cs_[1] - v0[3] * sn[1]; w0[3] = v0[3] * cs_[1] + v0[2] * sn[1];
;                                 w1[0] = v1[0] * cs_[2] - v1[1] * sn[2]; w1[1] = v1[1] * cs_[2] + v1[0] * sn[2];
;                                 w1[2] = v1[2] * cs_[3] - v1[3] * sn[3]; w1[3] = v1[3] * cs_[3] + v1[2] * sn[3];
;                                 v0 = w0; v1 = w1;
;                             }
;                             v0 = v0 * sc; v1 = v1 * sc;
;                         }
;                         u32x4 w; w.x = cvt_pk_bf16(v0[0], v0[1]); w.y = cvt_pk_bf16(v0[2], v0[3]); w.z = cvt_pk_bf16(v1[0], v1[1]); w.w = cvt_pk_bf16(v1[2], v1[3]);
.Lepi_relu2:
	v_lshlrev_b32_e32 v188, 2, v232
	global_load_dwordx4 v[144:147], v188, s[20:21] offset:512
	global_load_dwordx4 v[148:151], v188, s[20:21] offset:528
	global_load_dwordx4 v[152:155], v188, s[46:47] offset:512
	global_load_dwordx4 v[156:159], v188, s[46:47] offset:528
	v_mul_lo_u32 v189, v236, s55
	v_add_lshl_u32 v222, v189, v232, 1
	s_lshl_b32 s0, s55, 5
	v_add_u32_e32 v223, s0, v222
	s_lshl_b32 s1, s55, 6
	v_add_u32_e32 v224, s1, v222
	s_add_i32 s1, s1, s0
	v_add_u32_e32 v225, s1, v222
	s_lshl_b32 s1, s55, 8
	v_add_u32_e32 v226, s1, v222
	v_add_u32_e32 v227, s1, v223
	v_add_u32_e32 v228, s1, v224
	v_add_u32_e32 v229, s1, v225
	s_waitcnt vmcnt(0)
	v_pk_fma_f32 v[176:177], v[220:221], v[166:167], v[126:127] op_sel_hi:[0,1,1] neg_lo:[1,0,0] neg_hi:[1,0,0]
	v_pk_fma_f32 v[180:181], v[220:221], v[164:165], v[124:125] op_sel_hi:[0,1,1] neg_lo:[1,0,0] neg_hi:[1,0,0]
	v_mov_b32_e32 v184, v221
	v_pk_fma_f32 v[178:179], v[184:185], v[176:177], v[174:175] op_sel_hi:[0,1,1]
	v_pk_fma_f32 v[176:177], v[184:185], v[180:181], v[172:173] op_sel_hi:[0,1,1]
	v_pk_fma_f32 v[180:181], v[220:221], v[162:163], v[122:123] op_sel_hi:[0,1,1] neg_lo:[1,0,0] neg_hi:[1,0,0]
	v_pk_fma_f32 v[186:187], v[220:221], v[160:161], v[120:121] op_sel_hi:[0,1,1] neg_lo:[1,0,0] neg_hi:[1,0,0]
	v_pk_fma_f32 v[182:183], v[184:185], v[180:181], v[170:171] op_sel_hi:[0,1,1]
	v_pk_fma_f32 v[180:181], v[184:185], v[186:187], v[168:169] op_sel_hi:[0,1,1]
	v_max_f32_e32 v176, 0, v176
	v_max_f32_e32 v177, 0, v177
	v_max_f32_e32 v178, 0, v178
	v_max_f32_e32 v179, 0, v179
	v_max_f32_e32 v180, 0, v180
	v_max_f32_e32 v181, 0, v181
	v_max_f32_e32 v182, 0, v182
	v_max_f32_e32 v183, 0, v183
	v_pk_mul_f32 v[176:177], v[176:177], v[176:177]
	v_pk_mul_f32 v[178:179], v[178:179], v[178:179]
	v_pk_mul_f32 v[180:181], v[180:181], v[180:181]
	v_pk_mul_f32 v[182:183], v[182:183], v[182:183]
	v_cvt_pk_bf16_f32 v128, v176, v177
	v_cvt_pk_bf16_f32 v129, v178, v179
	v_cvt_pk_bf16_f32 v130, v180, v181
	v_cvt_pk_bf16_f32 v131, v182, v183
	global_store_dwordx4 v222, v[128:131], s[50:51] nt
	v_pk_fma_f32 v[176:177], v[218:219], v[166:167], v[118:119] op_sel_hi:[0,1,1] neg_lo:[1,0,0] neg_hi:[1,0,0]
	v_pk_fma_f32 v[180:181], v[218:219], v[164:165], v[116:117] op_sel_hi:[0,1,1] neg_lo:[1,0,0] neg_hi:[1,0,0]
	v_mov_b32_e32 v184, v219
	v_pk_fma_f32 v[178:179], v[184:185], v[176:177], v[174:175] op_sel_hi:[0,1,1]
	v_pk_fma_f32 v[176:177], v[184:185], v[180:181], v[172:173] op_sel_hi:[0,1,1]
	v_pk_fma_f32 v[180:181], v[218:219], v[162:163], v[114:115] op_sel_hi:[0,1,1] neg_lo:[1,0,0] neg_hi:[1,0,0]
	v_pk_fma_f32 v[186:187], v[218:219], v[160:161], v[112:113] op_sel_hi:[0,1,1] neg_lo:[1,0,0] neg_hi:[1,0,0]
	v_pk_fma_f32 v[182:183], v[184:185], v[180:181], v[170:171] op_sel_hi:[0,1,1]
	v_pk_fma_f32 v[180:181], v[184:185], v[186:187], v[168:169] op_sel_hi:[0,1,1]
	v_max_f32_e32 v176, 0, v176
	v_max_f32_e32 v177, 0, v177
	v_max_f32_e32 v178, 0, v178
	v_max_f32_e32 v179, 0, v179
	v_max_f32_e32 v180, 0, v180
	v_max_f32_e32 v181, 0, v181
	v_max_f32_e32 v182, 0, v182
	v_max_f32_e32 v183, 0, v183
	v_pk_mul_f32 v[176:177], v[176:177], v[176:177]
	v_pk_mul_f32 v[178:179], v[178:179], v[178:179]
	v_pk_mul_f32 v[180:181], v[180:181], v[180:181]
	v_pk_mul_f32 v[182:183], v[182:183], v[182:183]
	v_cvt_pk_bf16_f32 v132, v176, v177
	v_cvt_pk_bf16_f32 v133, v178, v179
	v_cvt_pk_bf16_f32 v134, v180, v181
	v_cvt_pk_bf16_f32 v135, v182, v183
	global_store_dwordx4 v223, v[132:135], s[50:51] nt
	v_pk_fma_f32 v[176:177], v[216:217], v[166:167], v[110:111] op_sel_hi:[0,1,1] neg_lo:[1,0,0] neg_hi:[1,0,0]
	v_pk_fma_f32 v[180:181], v[216:217], v[164:165], v[108:109] op_sel_hi:[0,1,1] neg_lo:[1,0,0] neg_hi:[1,0,0]
	v_mov_b32_e32 v184, v217
	v_pk_fma_f32 v[178:179], v[184:185], v[176:177], v[174:175] op_sel_hi:[0,1,1]
	v_pk_fma_f32 v[176:177], v[184:185], v[180:181], v[172:173] op_sel_hi:[0,1,1]
	v_pk_fma_f32 v[180:181], v[216:217], v[162:163], v[106:107] op_sel_hi:[0,1,1] neg_lo:[1,0,0] neg_hi:[1,0,0]
	v_pk_fma_f32 v[186:187], v[216:217], v[160:161], v[104:105] op_sel_hi:[0,1,1] neg_lo:[1,0,0] neg_hi:[1,0,0]
	v_pk_fma_f32 v[182:183], v[184:185], v[180:181], v[170:171] op_sel_hi:[0,1,1]
	v_pk_fma_f32 v[180:181], v[184:185], v[186:187], v[168:169] op_sel_hi:[0,1,1]
	v_max_f32_e32 v176, 0, v176
	v_max_f32_e32 v177, 0, v177
	v_max_f32_e32 v178, 0, v178
	v_max_f32_e32 v179, 0, v179
	v_max_f32_e32 v180, 0, v180
	v_max_f32_e32 v181, 0, v181
	v_max_f32_e32 v182, 0, v182
	v_max_f32_e32 v183, 0, v183
	v_pk_mul_f32 v[176:177], v[176:177], v[176:177]
	v_pk_mul_f32 v[178:179], v[178:179], v[178:179]
	v_pk_mul_f32 v[180:181], v[180:181], v[180:181]
	v_pk_mul_f32 v[182:183], v[182:183], v[182:183]
	v_cvt_pk_bf16_f32 v136, v176, v177
	v_cvt_pk_bf16_f32 v137, v178, v179
	v_cvt_pk_bf16_f32 v138, v180, v181
	v_cvt_pk_bf16_f32 v139, v182, v183
	global_store_dwordx4 v224, v[136:139], s[50:51] nt
	v_pk_fma_f32 v[176:177], v[214:215], v[166:167], v[102:103] op_sel_hi:[0,1,1] neg_lo:[1,0,0] neg_hi:[1,0,0]
	v_pk_fma_f32 v[180:181], v[214:215], v[164:165], v[100:101] op_sel_hi:[0,1,1] neg_lo:[1,0,0] neg_hi:[1,0,0]
	v_mov_b32_e32 v184, v215
	v_pk_fma_f32 v[178:179], v[184:185], v[176:177], v[174:175] op_sel_hi:[0,1,1]
	v_pk_fma_f32 v[176:177], v[184:185], v[180:181], v[172:173] op_sel_hi:[0,1,1]
	v_pk_fma_f32 v[180:181], v[214:215], v[162:163], v[98:99] op_sel_hi:[0,1,1] neg_lo:[1,0,0] neg_hi:[1,0,0]
	v_pk_fma_f32 v[186:187], v[214:215], v[160:161], v[96:97] op_sel_hi:[0,1,1] neg_lo:[1,0,0] neg_hi:[1,0,0]
	v_pk_fma_f32 v[182:183], v[184:185], v[180:181], v[170:171] op_sel_hi:[0,1,1]
	v_pk_fma_f32 v[180:181], v[184:185], v[186:187], v[168:169] op_sel_hi:[0,1,1]
; __device__ __forceinline__ unsigned cvt_pk_bf16(float lo, float hi) { unsigned r; asm volatile("v_cvt_pk_bf16_f32 %0, %1, %2" : "=v"(r) : "v"(lo), "v"(hi)); return r; }
;     __device__ __forceinline__ void operator()(const f32x4 (&acc)[2][2][4][2], const Unit& u, int wr, int wc, int fr_in, int fq_in) const {
;     ...
;                 for (int m = 0; m < 4; ++m) {
;                     const int row = row0 + ai * HALF + m * 16;
;                     f32x4 v0 = acc[ai][bj][m][0], v1 = acc[ai][bj][m][1];
;                     if (lnin) { const float mm = mu[ai * 4 + m], rr = rs[ai * 4 + m]; v0 = (v0 - cs0 * mm) * rr + bw0; v1 = (v1 - cs1 * mm) * rr + bw1; }
;                     if (mode == EM_F32) { const unsigned ob = (unsigned)(row * ldo + c) * 4u; *(f32x4*)((char*)Of + ob) = v0; *(f32x4*)((char*)Of + ob + 16u) = v1; }
;                     else {
;                         if (mode == EM_RELU2) {
; #pragma unroll
;                             for (int e = 0; e < 4; ++e) { const float a = fmaxf(v0[e], 0.f), b = fmaxf(v1[e], 0.f); v0[e] = a * a; v1[e] = b * b; }
;                         } else if (mode == EM_QKVA || mode == EM_UQ) {
;                             if (rope) {
;                                 const f32x4 cs_ = rc[m], sn = rsn[m];
;                                 f32x4 w0, w1;
;                                 w0[0] = v0[0] * cs_[0] - v0[1] * sn[0]; w0[1] = v0[1] * cs_[0] + v0[0] * sn[0];
;                                 w0[2] = v0[2] * cs_[1] - v0[3] * sn[1]; w0[3] = v0[3] * cs_[1] + v0[2] * sn[1];
;                                 w1[0] = v1[0] * cs_[2] - v1[1] * sn[2]; w1[1] = v1[1] * cs_[2] + v1[0] * sn[2];
;                                 w1[2] = v1[2] * cs_[3] - v1[3] * sn[3]; w1[3] = v1[3] * cs_[3] + v1[2] * sn[3];
;                                 v0 = w0; v1 = w1;
;                             }
;                             v0 = v0 * sc; v1 = v1 * sc;
;                         }
;                         u32x4 w; w.x = cvt_pk_bf16(v0[0], v0[1]); w.y = cvt_pk_bf16(v0[2], v0[3]); w.z = cvt_pk_bf16(v1[0], v1[1]); w.w = cvt_pk_bf16(v1[2], v1[3]);
;                         { u32x4* dp = (u32x4*)((char*)Ob + (unsigned)(row * ldo + c) * 2u); if (mode == EM_RELU2) { asm volatile("global_store_dwordx4 %0, %1, %2 nt\n\ts_nop 1" :: "v"((unsigned)(row * ldo + c) * 2u), "v"(w), "s"(Ob) : "memory"); } else *dp = w; }
	v_max_f32_e32 v176, 0, v176
	v_max_f32_e32 v177, 0, v177
	v_max_f32_e32 v178, 0, v178
	v_max_f32_e32 v179, 0, v179
	v_max_f32_e32 v180, 0, v180
	v_max_f32_e32 v181, 0, v181
	v_max_f32_e32 v182, 0, v182
	v_max_f32_e32 v183, 0, v183
	v_pk_mul_f32 v[176:177], v[176:177], v[176:177]
	v_pk_mul_f32 v[178:179], v[178:179], v[178:179]
	v_pk_mul_f32 v[180:181], v[180:181], v[180:181]
	v_pk_mul_f32 v[182:183], v[182:183], v[182:183]
	v_cvt_pk_bf16_f32 v140, v176, v177
	v_cvt_pk_bf16_f32 v141, v178, v179
	v_cvt_pk_bf16_f32 v142, v180, v181
	v_cvt_pk_bf16_f32 v143, v182, v183
	global_store_dwordx4 v225, v[140:143], s[50:51] nt
	v_pk_fma_f32 v[176:177], v[212:213], v[166:167], v[62:63] op_sel_hi:[0,1,1] neg_lo:[1,0,0] neg_hi:[1,0,0]
	v_pk_fma_f32 v[180:181], v[212:213], v[164:165], v[60:61] op_sel_hi:[0,1,1] neg_lo:[1,0,0] neg_hi:[1,0,0]
	v_mov_b32_e32 v184, v213
	v_pk_fma_f32 v[178:179], v[184:185], v[176:177], v[174:175] op_sel_hi:[0,1,1]
	v_pk_fma_f32 v[176:177], v[184:185], v[180:181], v[172:173] op_sel_hi:[0,1,1]
	v_pk_fma_f32 v[180:181], v[212:213], v[162:163], v[58:59] op_sel_hi:[0,1,1] neg_lo:[1,0,0] neg_hi:[1,0,0]
	v_pk_fma_f32 v[186:187], v[212:213], v[160:161], v[56:57] op_sel_hi:[0,1,1] neg_lo:[1,0,0] neg_hi:[1,0,0]
	v_pk_fma_f32 v[182:183], v[184:185], v[180:181], v[170:171] op_sel_hi:[0,1,1]
	v_pk_fma_f32 v[180:181], v[184:185], v[186:187], v[168:169] op_sel_hi:[0,1,1]
	v_max_f32_e32 v176, 0, v176
	v_max_f32_e32 v177, 0, v177
	v_max_f32_e32 v178, 0, v178
	v_max_f32_e32 v179, 0, v179
	v_max_f32_e32 v180, 0, v180
	v_max_f32_e32 v181, 0, v181
	v_max_f32_e32 v182, 0, v182
	v_max_f32_e32 v183, 0, v183
	v_pk_mul_f32 v[176:177], v[176:177], v[176:177]
	v_pk_mul_f32 v[178:179], v[178:179], v[178:179]
	v_pk_mul_f32 v[180:181], v[180:181], v[180:181]
	v_pk_mul_f32 v[182:183], v[182:183], v[182:183]
	v_cvt_pk_bf16_f32 v128, v176, v177
	v_cvt_pk_bf16_f32 v129, v178, v179
	v_cvt_pk_bf16_f32 v130, v180, v181
	v_cvt_pk_bf16_f32 v131, v182, v183
	global_store_dwordx4 v226, v[128:131], s[50:51] nt
	v_pk_fma_f32 v[176:177], v[210:211], v[166:167], v[54:55] op_sel_hi:[0,1,1] neg_lo:[1,0,0] neg_hi:[1,0,0]
	v_pk_fma_f32 v[180:181], v[210:211], v[164:165], v[52:53] op_sel_hi:[0,1,1] neg_lo:[1,0,0] neg_hi:[1,0,0]
	v_mov_b32_e32 v184, v211
	v_pk_fma_f32 v[178:179], v[184:185], v[176:177], v[174:175] op_sel_hi:[0,1,1]
	v_pk_fma_f32 v[176:177], v[184:185], v[180:181], v[172:173] op_sel_hi:[0,1,1]
	v_pk_fma_f32 v[180:181], v[210:211], v[162:163], v[50:51] op_sel_hi:[0,1,1] neg_lo:[1,0,0] neg_hi:[1,0,0]
	v_pk_fma_f32 v[186:187], v[210:211], v[160:161], v[48:49] op_sel_hi:[0,1,1] neg_lo:[1,0,0] neg_hi:[1,0,0]
	v_pk_fma_f32 v[182:183], v[184:185], v[180:181], v[170:171] op_sel_hi:[0,1,1]
	v_pk_fma_f32 v[180:181], v[184:185], v[186:187], v[168:169] op_sel_hi:[0,1,1]
	v_max_f32_e32 v176, 0, v176
	v_max_f32_e32 v177, 0, v177
	v_max_f32_e32 v178, 0, v178
	v_max_f32_e32 v179, 0, v179
	v_max_f32_e32 v180, 0, v180
	v_max_f32_e32 v181, 0, v181
	v_max_f32_e32 v182, 0, v182
	v_max_f32_e32 v183, 0, v183
	v_pk_mul_f32 v[176:177], v[176:177], v[176:177]
	v_pk_mul_f32 v[178:179], v[178:179], v[178:179]
	v_pk_mul_f32 v[180:181], v[180:181], v[180:181]
	v_pk_mul_f32 v[182:183], v[182:183], v[182:183]
	v_cvt_pk_bf16_f32 v132, v176, v177
	v_cvt_pk_bf16_f32 v133, v178, v179
	v_cvt_pk_bf16_f32 v134, v180, v181
	v_cvt_pk_bf16_f32 v135, v182, v183
	global_store_dwordx4 v227, v[132:135], s[50:51] nt
	v_pk_fma_f32 v[176:177], v[208:209], v[166:167], v[46:47] op_sel_hi:[0,1,1] neg_lo:[1,0,0] neg_hi:[1,0,0]
	v_pk_fma_f32 v[180:181], v[208:209], v[164:165], v[44:45] op_sel_hi:[0,1,1] neg_lo:[1,0,0] neg_hi:[1,0,0]
	v_mov_b32_e32 v184, v209
	v_pk_fma_f32 v[178:179], v[184:185], v[176:177], v[174:175] op_sel_hi:[0,1,1]
	v_pk_fma_f32 v[176:177], v[184:185], v[180:181], v[172:173] op_sel_hi:[0,1,1]
	v_pk_fma_f32 v[180:181], v[208:209], v[162:163], v[42:43] op_sel_hi:[0,1,1] neg_lo:[1,0,0] neg_hi:[1,0,0]
	v_pk_fma_f32 v[186:187], v[208:209], v[160:161], v[40:41] op_sel_hi:[0,1,1] neg_lo:[1,0,0] neg_hi:[1,0,0]
	v_pk_fma_f32 v[182:183], v[184:185], v[180:181], v[170:171] op_sel_hi:[0,1,1]
	v_pk_fma_f32 v[180:181], v[184:185], v[186:187], v[168:169] op_sel_hi:[0,1,1]
	v_max_f32_e32 v176, 0, v176
	v_max_f32_e32 v177, 0, v177
	v_max_f32_e32 v178, 0, v178
	v_max_f32_e32 v179, 0, v179
	v_max_f32_e32 v180, 0, v180
	v_max_f32_e32 v181, 0, v181
	v_max_f32_e32 v182, 0, v182
	v_max_f32_e32 v183, 0, v183
	v_pk_mul_f32 v[176:177], v[176:177], v[176:177]
	v_pk_mul_f32 v[178:179], v[178:179], v[178:179]
	v_pk_mul_f32 v[180:181], v[180:181], v[180:181]
	v_pk_mul_f32 v[182:183], v[182:183], v[182:183]
	v_cvt_pk_bf16_f32 v136, v176, v177
	v_cvt_pk_bf16_f32 v137, v178, v179
	v_cvt_pk_bf16_f32 v138, v180, v181
	v_cvt_pk_bf16_f32 v139, v182, v183
	global_store_dwordx4 v228, v[136:139], s[50:51] nt
	v_pk_fma_f32 v[176:177], v[206:207], v[166:167], v[38:39] op_sel_hi:[0,1,1] neg_lo:[1,0,0] neg_hi:[1,0,0]
	v_pk_fma_f32 v[180:181], v[206:207], v[164:165], v[36:37] op_sel_hi:[0,1,1] neg_lo:[1,0,0] neg_hi:[1,0,0]
	v_mov_b32_e32 v184, v207
	v_pk_fma_f32 v[178:179], v[184:185], v[176:177], v[174:175] op_sel_hi:[0,1,1]
	v_pk_fma_f32 v[176:177], v[184:185], v[180:181], v[172:173] op_sel_hi:[0,1,1]
	v_pk_fma_f32 v[180:181], v[206:207], v[162:163], v[34:35] op_sel_hi:[0,1,1] neg_lo:[1,0,0] neg_hi:[1,0,0]
	v_pk_fma_f32 v[186:187], v[206:207], v[160:161], v[32:33] op_sel_hi:[0,1,1] neg_lo:[1,0,0] neg_hi:[1,0,0]
	v_pk_fma_f32 v[182:183], v[184:185], v[180:181], v[170:171] op_sel_hi:[0,1,1]
	v_pk_fma_f32 v[180:181], v[184:185], v[186:187], v[168:169] op_sel_hi:[0,1,1]
	v_max_f32_e32 v176, 0, v176
	v_max_f32_e32 v177, 0, v177
; __device__ __forceinline__ unsigned cvt_pk_bf16(float lo, float hi) { unsigned r; asm volatile("v_cvt_pk_bf16_f32 %0, %1, %2" : "=v"(r) : "v"(lo), "v"(hi)); return r; }
;     __device__ __forceinline__ void operator()(const f32x4 (&acc)[2][2][4][2], const Unit& u, int wr, int wc, int fr_in, int fq_in) const {
;     ...
;                 for (int m = 0; m < 4; ++m) {
;                     const int row = row0 + ai * HALF + m * 16;
;                     f32x4 v0 = acc[ai][bj][m][0], v1 = acc[ai][bj][m][1];
;                     if (lnin) { const float mm = mu[ai * 4 + m], rr = rs[ai * 4 + m]; v0 = (v0 - cs0 * mm) * rr + bw0; v1 = (v1 - cs1 * mm) * rr + bw1; }
;                     if (mode == EM_F32) { const unsigned ob = (unsigned)(row * ldo + c) * 4u; *(f32x4*)((char*)Of + ob) = v0; *(f32x4*)((char*)Of + ob + 16u) = v1; }
;                     else {
;                         if (mode == EM_RELU2) {
; #pragma unroll
;                             for (int e = 0; e < 4; ++e) { const float a = fmaxf(v0[e], 0.f), b = fmaxf(v1[e], 0.f); v0[e] = a * a; v1[e] = b * b; }
;                         } else if (mode == EM_QKVA || mode == EM_UQ) {
;                             if (rope) {
;                                 const f32x4 cs_ = rc[m], sn = rsn[m];
;                                 f32x4 w0, w1;
;                                 w0[0] = v0[0] * cs_[0] - v0[1] * sn[0]; w0[1] = v0[1] * cs_[0] + v0[0] * sn[0];
;                                 w0[2] = v0[2] * cs_[1] - v0[3] * sn[1]; w0[3] = v0[3] * cs_[1] + v0[2] * sn[1];
;                                 w1[0] = v1[0] * cs_[2] - v1[1] * sn[2]; w1[1] = v1[1] * cs_[2] + v1[0] * sn[2];
;                                 w1[2] = v1[2] * cs_[3] - v1[3] * sn[3]; w1[3] = v1[3] * cs_[3] + v1[2] * sn[3];
;                                 v0 = w0; v1 = w1;
;                             }
;                             v0 = v0 * sc; v1 = v1 * sc;
;                         }
;                         u32x4 w; w.x = cvt_pk_bf16(v0[0], v0[1]); w.y = cvt_pk_bf16(v0[2], v0[3]); w.z = cvt_pk_bf16(v1[0], v1[1]); w.w = cvt_pk_bf16(v1[2], v1[3]);
;                         { u32x4* dp = (u32x4*)((char*)Ob + (unsigned)(row * ldo + c) * 2u); if (mode == EM_RELU2) { asm volatile("global_store_dwordx4 %0, %1, %2 nt\n\ts_nop 1" :: "v"((unsigned)(row * ldo + c) * 2u), "v"(w), "s"(Ob) : "memory"); } else *dp = w; }
	v_max_f32_e32 v178, 0, v178
	v_max_f32_e32 v179, 0, v179
	v_max_f32_e32 v180, 0, v180
	v_max_f32_e32 v181, 0, v181
	v_max_f32_e32 v182, 0, v182
	v_max_f32_e32 v183, 0, v183
	v_pk_mul_f32 v[176:177], v[176:177], v[176:177]
	v_pk_mul_f32 v[178:179], v[178:179], v[178:179]
	v_pk_mul_f32 v[180:181], v[180:181], v[180:181]
	v_pk_mul_f32 v[182:183], v[182:183], v[182:183]
	v_cvt_pk_bf16_f32 v140, v176, v177
	v_cvt_pk_bf16_f32 v141, v178, v179
	v_cvt_pk_bf16_f32 v142, v180, v181
	v_cvt_pk_bf16_f32 v143, v182, v183
	global_store_dwordx4 v229, v[140:143], s[50:51] nt
	v_pk_fma_f32 v[176:177], v[220:221], v[146:147], v[94:95] op_sel_hi:[0,1,1] neg_lo:[1,0,0] neg_hi:[1,0,0]
	v_pk_fma_f32 v[180:181], v[220:221], v[144:145], v[92:93] op_sel_hi:[0,1,1] neg_lo:[1,0,0] neg_hi:[1,0,0]
	v_mov_b32_e32 v184, v221
	v_pk_fma_f32 v[178:179], v[184:185], v[176:177], v[154:155] op_sel_hi:[0,1,1]
	v_pk_fma_f32 v[176:177], v[184:185], v[180:181], v[152:153] op_sel_hi:[0,1,1]
	v_pk_fma_f32 v[180:181], v[220:221], v[150:151], v[90:91] op_sel_hi:[0,1,1] neg_lo:[1,0,0] neg_hi:[1,0,0]
	v_pk_fma_f32 v[186:187], v[220:221], v[148:149], v[88:89] op_sel_hi:[0,1,1] neg_lo:[1,0,0] neg_hi:[1,0,0]
	v_pk_fma_f32 v[182:183], v[184:185], v[180:181], v[158:159] op_sel_hi:[0,1,1]
	v_pk_fma_f32 v[180:181], v[184:185], v[186:187], v[156:157] op_sel_hi:[0,1,1]
	v_max_f32_e32 v176, 0, v176
	v_max_f32_e32 v177, 0, v177
	v_max_f32_e32 v178, 0, v178
	v_max_f32_e32 v179, 0, v179
	v_max_f32_e32 v180, 0, v180
	v_max_f32_e32 v181, 0, v181
	v_max_f32_e32 v182, 0, v182
	v_max_f32_e32 v183, 0, v183
	v_pk_mul_f32 v[176:177], v[176:177], v[176:177]
	v_pk_mul_f32 v[178:179], v[178:179], v[178:179]
	v_pk_mul_f32 v[180:181], v[180:181], v[180:181]
	v_pk_mul_f32 v[182:183], v[182:183], v[182:183]
	v_cvt_pk_bf16_f32 v128, v176, v177
	v_cvt_pk_bf16_f32 v129, v178, v179
	v_cvt_pk_bf16_f32 v130, v180, v181
	v_cvt_pk_bf16_f32 v131, v182, v183
	global_store_dwordx4 v222, v[128:131], s[50:51] offset:256 nt
	v_pk_fma_f32 v[176:177], v[218:219], v[146:147], v[86:87] op_sel_hi:[0,1,1] neg_lo:[1,0,0] neg_hi:[1,0,0]
	v_pk_fma_f32 v[180:181], v[218:219], v[144:145], v[84:85] op_sel_hi:[0,1,1] neg_lo:[1,0,0] neg_hi:[1,0,0]
	v_mov_b32_e32 v184, v219
	v_pk_fma_f32 v[178:179], v[184:185], v[176:177], v[154:155] op_sel_hi:[0,1,1]
	v_pk_fma_f32 v[176:177], v[184:185], v[180:181], v[152:153] op_sel_hi:[0,1,1]
	v_pk_fma_f32 v[180:181], v[218:219], v[150:151], v[82:83] op_sel_hi:[0,1,1] neg_lo:[1,0,0] neg_hi:[1,0,0]
	v_pk_fma_f32 v[186:187], v[218:219], v[148:149], v[80:81] op_sel_hi:[0,1,1] neg_lo:[1,0,0] neg_hi:[1,0,0]
	v_pk_fma_f32 v[182:183], v[184:185], v[180:181], v[158:159] op_sel_hi:[0,1,1]
	v_pk_fma_f32 v[180:181], v[184:185], v[186:187], v[156:157] op_sel_hi:[0,1,1]
	v_max_f32_e32 v176, 0, v176
	v_max_f32_e32 v177, 0, v177
	v_max_f32_e32 v178, 0, v178
	v_max_f32_e32 v179, 0, v179
	v_max_f32_e32 v180, 0, v180
	v_max_f32_e32 v181, 0, v181
	v_max_f32_e32 v182, 0, v182
	v_max_f32_e32 v183, 0, v183
	v_pk_mul_f32 v[176:177], v[176:177], v[176:177]
	v_pk_mul_f32 v[178:179], v[178:179], v[178:179]
	v_pk_mul_f32 v[180:181], v[180:181], v[180:181]
	v_pk_mul_f32 v[182:183], v[182:183], v[182:183]
	v_cvt_pk_bf16_f32 v132, v176, v177
	v_cvt_pk_bf16_f32 v133, v178, v179
	v_cvt_pk_bf16_f32 v134, v180, v181
	v_cvt_pk_bf16_f32 v135, v182, v183
	global_store_dwordx4 v223, v[132:135], s[50:51] offset:256 nt
	v_pk_fma_f32 v[176:177], v[216:217], v[146:147], v[78:79] op_sel_hi:[0,1,1] neg_lo:[1,0,0] neg_hi:[1,0,0]
	v_pk_fma_f32 v[180:181], v[216:217], v[144:145], v[76:77] op_sel_hi:[0,1,1] neg_lo:[1,0,0] neg_hi:[1,0,0]
	v_mov_b32_e32 v184, v217
	v_pk_fma_f32 v[178:179], v[184:185], v[176:177], v[154:155] op_sel_hi:[0,1,1]
	v_pk_fma_f32 v[176:177], v[184:185], v[180:181], v[152:153] op_sel_hi:[0,1,1]
	v_pk_fma_f32 v[180:181], v[216:217], v[150:151], v[74:75] op_sel_hi:[0,1,1] neg_lo:[1,0,0] neg_hi:[1,0,0]
	v_pk_fma_f32 v[186:187], v[216:217], v[148:149], v[72:73] op_sel_hi:[0,1,1] neg_lo:[1,0,0] neg_hi:[1,0,0]
	v_pk_fma_f32 v[182:183], v[184:185], v[180:181], v[158:159] op_sel_hi:[0,1,1]
	v_pk_fma_f32 v[180:181], v[184:185], v[186:187], v[156:157] op_sel_hi:[0,1,1]
	v_max_f32_e32 v176, 0, v176
	v_max_f32_e32 v177, 0, v177
	v_max_f32_e32 v178, 0, v178
	v_max_f32_e32 v179, 0, v179
	v_max_f32_e32 v180, 0, v180
	v_max_f32_e32 v181, 0, v181
	v_max_f32_e32 v182, 0, v182
	v_max_f32_e32 v183, 0, v183
	v_pk_mul_f32 v[176:177], v[176:177], v[176:177]
	v_pk_mul_f32 v[178:179], v[178:179], v[178:179]
	v_pk_mul_f32 v[180:181], v[180:181], v[180:181]
	v_pk_mul_f32 v[182:183], v[182:183], v[182:183]
	v_cvt_pk_bf16_f32 v136, v176, v177
	v_cvt_pk_bf16_f32 v137, v178, v179
	v_cvt_pk_bf16_f32 v138, v180, v181
	v_cvt_pk_bf16_f32 v139, v182, v183
	global_store_dwordx4 v224, v[136:139], s[50:51] offset:256 nt
	v_pk_fma_f32 v[176:177], v[214:215], v[146:147], v[70:71] op_sel_hi:[0,1,1] neg_lo:[1,0,0] neg_hi:[1,0,0]
	v_pk_fma_f32 v[180:181], v[214:215], v[144:145], v[68:69] op_sel_hi:[0,1,1] neg_lo:[1,0,0] neg_hi:[1,0,0]
	v_mov_b32_e32 v184, v215
	v_pk_fma_f32 v[178:179], v[184:185], v[176:177], v[154:155] op_sel_hi:[0,1,1]
	v_pk_fma_f32 v[176:177], v[184:185], v[180:181], v[152:153] op_sel_hi:[0,1,1]
	v_pk_fma_f32 v[180:181], v[214:215], v[150:151], v[66:67] op_sel_hi:[0,1,1] neg_lo:[1,0,0] neg_hi:[1,0,0]
	v_pk_fma_f32 v[186:187], v[214:215], v[148:149], v[64:65] op_sel_hi:[0,1,1] neg_lo:[1,0,0] neg_hi:[1,0,0]
	v_pk_fma_f32 v[182:183], v[184:185], v[180:181], v[158:159] op_sel_hi:[0,1,1]
	v_pk_fma_f32 v[180:181], v[184:185], v[186:187], v[156:157] op_sel_hi:[0,1,1]
	v_max_f32_e32 v176, 0, v176
	v_max_f32_e32 v177, 0, v177
	v_max_f32_e32 v178, 0, v178
; __device__ __forceinline__ unsigned cvt_pk_bf16(float lo, float hi) { unsigned r; asm volatile("v_cvt_pk_bf16_f32 %0, %1, %2" : "=v"(r) : "v"(lo), "v"(hi)); return r; }
;     __device__ __forceinline__ void operator()(const f32x4 (&acc)[2][2][4][2], const Unit& u, int wr, int wc, int fr_in, int fq_in) const {
;     ...
;                 for (int m = 0; m < 4; ++m) {
;                     const int row = row0 + ai * HALF + m * 16;
;                     f32x4 v0 = acc[ai][bj][m][0], v1 = acc[ai][bj][m][1];
;                     if (lnin) { const float mm = mu[ai * 4 + m], rr = rs[ai * 4 + m]; v0 = (v0 - cs0 * mm) * rr + bw0; v1 = (v1 - cs1 * mm) * rr + bw1; }
;                     if (mode == EM_F32) { const unsigned ob = (unsigned)(row * ldo + c) * 4u; *(f32x4*)((char*)Of + ob) = v0; *(f32x4*)((char*)Of + ob + 16u) = v1; }
;                     else {
;                         if (mode == EM_RELU2) {
; #pragma unroll
;                             for (int e = 0; e < 4; ++e) { const float a = fmaxf(v0[e], 0.f), b = fmaxf(v1[e], 0.f); v0[e] = a * a; v1[e] = b * b; }
;                         } else if (mode == EM_QKVA || mode == EM_UQ) {
;                             if (rope) {
;                                 const f32x4 cs_ = rc[m], sn = rsn[m];
;                                 f32x4 w0, w1;
;                                 w0[0] = v0[0] * cs_[0] - v0[1] * sn[0]; w0[1] = v0[1] * cs_[0] + v0[0] * sn[0];
;                                 w0[2] = v0[2] * cs_[1] - v0[3] * sn[1]; w0[3] = v0[3] * cs_[1] + v0[2] * sn[1];
;                                 w1[0] = v1[0] * cs_[2] - v1[1] * sn[2]; w1[1] = v1[1] * cs_[2] + v1[0] * sn[2];
;                                 w1[2] = v1[2] * cs_[3] - v1[3] * sn[3]; w1[3] = v1[3] * cs_[3] + v1[2] * sn[3];
;                                 v0 = w0; v1 = w1;
;                             }
;                             v0 = v0 * sc; v1 = v1 * sc;
;                         }
;                         u32x4 w; w.x = cvt_pk_bf16(v0[0], v0[1]); w.y = cvt_pk_bf16(v0[2], v0[3]); w.z = cvt_pk_bf16(v1[0], v1[1]); w.w = cvt_pk_bf16(v1[2], v1[3]);
;                         { u32x4* dp = (u32x4*)((char*)Ob + (unsigned)(row * ldo + c) * 2u); if (mode == EM_RELU2) { asm volatile("global_store_dwordx4 %0, %1, %2 nt\n\ts_nop 1" :: "v"((unsigned)(row * ldo + c) * 2u), "v"(w), "s"(Ob) : "memory"); } else *dp = w; }
	v_max_f32_e32 v179, 0, v179
	v_max_f32_e32 v180, 0, v180
	v_max_f32_e32 v181, 0, v181
	v_max_f32_e32 v182, 0, v182
	v_max_f32_e32 v183, 0, v183
	v_pk_mul_f32 v[176:177], v[176:177], v[176:177]
	v_pk_mul_f32 v[178:179], v[178:179], v[178:179]
	v_pk_mul_f32 v[180:181], v[180:181], v[180:181]
	v_pk_mul_f32 v[182:183], v[182:183], v[182:183]
	v_cvt_pk_bf16_f32 v140, v176, v177
	v_cvt_pk_bf16_f32 v141, v178, v179
	v_cvt_pk_bf16_f32 v142, v180, v181
	v_cvt_pk_bf16_f32 v143, v182, v183
	global_store_dwordx4 v225, v[140:143], s[50:51] offset:256 nt
	v_pk_fma_f32 v[176:177], v[212:213], v[146:147], v[30:31] op_sel_hi:[0,1,1] neg_lo:[1,0,0] neg_hi:[1,0,0]
	v_pk_fma_f32 v[180:181], v[212:213], v[144:145], v[28:29] op_sel_hi:[0,1,1] neg_lo:[1,0,0] neg_hi:[1,0,0]
	v_mov_b32_e32 v184, v213
	v_pk_fma_f32 v[178:179], v[184:185], v[176:177], v[154:155] op_sel_hi:[0,1,1]
	v_pk_fma_f32 v[176:177], v[184:185], v[180:181], v[152:153] op_sel_hi:[0,1,1]
	v_pk_fma_f32 v[180:181], v[212:213], v[150:151], v[26:27] op_sel_hi:[0,1,1] neg_lo:[1,0,0] neg_hi:[1,0,0]
	v_pk_fma_f32 v[186:187], v[212:213], v[148:149], v[24:25] op_sel_hi:[0,1,1] neg_lo:[1,0,0] neg_hi:[1,0,0]
	v_pk_fma_f32 v[182:183], v[184:185], v[180:181], v[158:159] op_sel_hi:[0,1,1]
	v_pk_fma_f32 v[180:181], v[184:185], v[186:187], v[156:157] op_sel_hi:[0,1,1]
	v_max_f32_e32 v176, 0, v176
	v_max_f32_e32 v177, 0, v177
	v_max_f32_e32 v178, 0, v178
	v_max_f32_e32 v179, 0, v179
	v_max_f32_e32 v180, 0, v180
	v_max_f32_e32 v181, 0, v181
	v_max_f32_e32 v182, 0, v182
	v_max_f32_e32 v183, 0, v183
	v_pk_mul_f32 v[176:177], v[176:177], v[176:177]
	v_pk_mul_f32 v[178:179], v[178:179], v[178:179]
	v_pk_mul_f32 v[180:181], v[180:181], v[180:181]
	v_pk_mul_f32 v[182:183], v[182:183], v[182:183]
	v_cvt_pk_bf16_f32 v128, v176, v177
	v_cvt_pk_bf16_f32 v129, v178, v179
	v_cvt_pk_bf16_f32 v130, v180, v181
	v_cvt_pk_bf16_f32 v131, v182, v183
	global_store_dwordx4 v226, v[128:131], s[50:51] offset:256 nt
	v_pk_fma_f32 v[176:177], v[210:211], v[146:147], v[22:23] op_sel_hi:[0,1,1] neg_lo:[1,0,0] neg_hi:[1,0,0]
	v_pk_fma_f32 v[180:181], v[210:211], v[144:145], v[20:21] op_sel_hi:[0,1,1] neg_lo:[1,0,0] neg_hi:[1,0,0]
	v_mov_b32_e32 v184, v211
	v_pk_fma_f32 v[178:179], v[184:185], v[176:177], v[154:155] op_sel_hi:[0,1,1]
	v_pk_fma_f32 v[176:177], v[184:185], v[180:181], v[152:153] op_sel_hi:[0,1,1]
	v_pk_fma_f32 v[180:181], v[210:211], v[150:151], v[18:19] op_sel_hi:[0,1,1] neg_lo:[1,0,0] neg_hi:[1,0,0]
	v_pk_fma_f32 v[186:187], v[210:211], v[148:149], v[16:17] op_sel_hi:[0,1,1] neg_lo:[1,0,0] neg_hi:[1,0,0]
	v_pk_fma_f32 v[182:183], v[184:185], v[180:181], v[158:159] op_sel_hi:[0,1,1]
	v_pk_fma_f32 v[180:181], v[184:185], v[186:187], v[156:157] op_sel_hi:[0,1,1]
	v_max_f32_e32 v176, 0, v176
	v_max_f32_e32 v177, 0, v177
	v_max_f32_e32 v178, 0, v178
	v_max_f32_e32 v179, 0, v179
	v_max_f32_e32 v180, 0, v180
	v_max_f32_e32 v181, 0, v181
	v_max_f32_e32 v182, 0, v182
	v_max_f32_e32 v183, 0, v183
	v_pk_mul_f32 v[176:177], v[176:177], v[176:177]
	v_pk_mul_f32 v[178:179], v[178:179], v[178:179]
	v_pk_mul_f32 v[180:181], v[180:181], v[180:181]
	v_pk_mul_f32 v[182:183], v[182:183], v[182:183]
	v_cvt_pk_bf16_f32 v132, v176, v177
	v_cvt_pk_bf16_f32 v133, v178, v179
	v_cvt_pk_bf16_f32 v134, v180, v181
	v_cvt_pk_bf16_f32 v135, v182, v183
	global_store_dwordx4 v227, v[132:135], s[50:51] offset:256 nt
	v_pk_fma_f32 v[176:177], v[208:209], v[146:147], v[14:15] op_sel_hi:[0,1,1] neg_lo:[1,0,0] neg_hi:[1,0,0]
	v_pk_fma_f32 v[180:181], v[208:209], v[144:145], v[12:13] op_sel_hi:[0,1,1] neg_lo:[1,0,0] neg_hi:[1,0,0]
	v_mov_b32_e32 v184, v209
	v_pk_fma_f32 v[178:179], v[184:185], v[176:177], v[154:155] op_sel_hi:[0,1,1]
	v_pk_fma_f32 v[176:177], v[184:185], v[180:181], v[152:153] op_sel_hi:[0,1,1]
	v_pk_fma_f32 v[180:181], v[208:209], v[150:151], v[10:11] op_sel_hi:[0,1,1] neg_lo:[1,0,0] neg_hi:[1,0,0]
	v_pk_fma_f32 v[186:187], v[208:209], v[148:149], v[8:9] op_sel_hi:[0,1,1] neg_lo:[1,0,0] neg_hi:[1,0,0]
	v_pk_fma_f32 v[182:183], v[184:185], v[180:181], v[158:159] op_sel_hi:[0,1,1]
	v_pk_fma_f32 v[180:181], v[184:185], v[186:187], v[156:157] op_sel_hi:[0,1,1]
	v_max_f32_e32 v176, 0, v176
	v_max_f32_e32 v177, 0, v177
	v_max_f32_e32 v178, 0, v178
	v_max_f32_e32 v179, 0, v179
	v_max_f32_e32 v180, 0, v180
	v_max_f32_e32 v181, 0, v181
	v_max_f32_e32 v182, 0, v182
	v_max_f32_e32 v183, 0, v183
	v_pk_mul_f32 v[176:177], v[176:177], v[176:177]
	v_pk_mul_f32 v[178:179], v[178:179], v[178:179]
	v_pk_mul_f32 v[180:181], v[180:181], v[180:181]
	v_pk_mul_f32 v[182:183], v[182:183], v[182:183]
	v_cvt_pk_bf16_f32 v136, v176, v177
	v_cvt_pk_bf16_f32 v137, v178, v179
	v_cvt_pk_bf16_f32 v138, v180, v181
	v_cvt_pk_bf16_f32 v139, v182, v183
	global_store_dwordx4 v228, v[136:139], s[50:51] offset:256 nt
	v_pk_fma_f32 v[176:177], v[206:207], v[146:147], v[6:7] op_sel_hi:[0,1,1] neg_lo:[1,0,0] neg_hi:[1,0,0]
	v_pk_fma_f32 v[180:181], v[206:207], v[144:145], v[4:5] op_sel_hi:[0,1,1] neg_lo:[1,0,0] neg_hi:[1,0,0]
	v_mov_b32_e32 v184, v207
	v_pk_fma_f32 v[178:179], v[184:185], v[176:177], v[154:155] op_sel_hi:[0,1,1]
	v_pk_fma_f32 v[176:177], v[184:185], v[180:181], v[152:153] op_sel_hi:[0,1,1]
	v_pk_fma_f32 v[180:181], v[206:207], v[150:151], v[2:3] op_sel_hi:[0,1,1] neg_lo:[1,0,0] neg_hi:[1,0,0]
	v_pk_fma_f32 v[186:187], v[206:207], v[148:149], v[0:1] op_sel_hi:[0,1,1] neg_lo:[1,0,0] neg_hi:[1,0,0]
	v_pk_fma_f32 v[182:183], v[184:185], v[180:181], v[158:159] op_sel_hi:[0,1,1]
	v_pk_fma_f32 v[180:181], v[184:185], v[186:187], v[156:157] op_sel_hi:[0,1,1]
	v_max_f32_e32 v176, 0, v176
	v_max_f32_e32 v177, 0, v177
	v_max_f32_e32 v178, 0, v178
	v_max_f32_e32 v179, 0, v179
	v_max_f32_e32 v180, 0, v180
	v_max_f32_e32 v181, 0, v181
	v_max_f32_e32 v182, 0, v182
	v_max_f32_e32 v183, 0, v183
	v_pk_mul_f32 v[176:177], v[176:177], v[176:177]
	v_pk_mul_f32 v[178:179], v[178:179], v[178:179]
	v_pk_mul_f32 v[180:181], v[180:181], v[180:181]
	v_pk_mul_f32 v[182:183], v[182:183], v[182:183]
	v_cvt_pk_bf16_f32 v140, v176, v177
	v_cvt_pk_bf16_f32 v141, v178, v179
	v_cvt_pk_bf16_f32 v142, v180, v181
	v_cvt_pk_bf16_f32 v143, v182, v183
	global_store_dwordx4 v229, v[140:143], s[50:51] offset:256 nt
	s_branch .LBB0_736
